# side job trimmed: row step in the lane offset (VALU in MFMA stream), item switch by constant address bumps (no s_load / full decode unless the column block changes)
# baseline (speedup 1.0000x reference)
.LBB0_1202:
	s_or_b64 exec, exec, s[6:7]
	s_waitcnt lgkmcnt(0)
	v_mov_b32_e32 v0, v234
	s_barrier
	v_mbcnt_lo_u32_b32 v223, -1, 0
	v_mbcnt_hi_u32_b32 v223, -1, v223
	v_and_b32_e32 v224, 7, v223
	v_lshrrev_b32_e32 v225, 3, v223
	v_lshlrev_b32_e32 v226, 4, v224
	v_lshl_add_u32 v223, v225, 18, v226
	v_mul_u32_u24_e32 v224, 0xac00, v224
	v_lshl_add_u32 v224, v225, 4, v224
	v_add_u32_e32 v224, 0x12f00000, v224
	v_mov_b32_e32 v220, 0
	v_mov_b32_e32 v225, 0
	v_mov_b32_e32 v252, 0
	v_mov_b32_e32 v253, 0
	v_cvt_f32_u32_e32 v244, s94
	v_rcp_iflag_f32_e32 v244, v244
	s_nop 1
	v_mul_f32_e32 v244, 0x4f7ffffe, v244
	v_cvt_u32_f32_e32 v244, v244
	s_nop 1
	v_readfirstlane_b32 s75, v244
	s_sub_i32 s76, 0, s94
	s_mul_i32 s76, s76, s75
	s_mul_hi_u32 s76, s75, s76
	s_add_i32 s75, s75, s76
	s_mov_b32 s77, 0x2b00
	s_mul_hi_u32 s76, s77, s75
	s_mul_i32 s98, s76, s94
	s_sub_i32 s77, s77, s98
	s_add_i32 s98, s76, 1
	s_sub_i32 s99, s77, s94
	s_cmp_ge_u32 s77, s94
	s_cselect_b32 s76, s98, s76
	s_cselect_b32 s77, s99, s77
	s_add_i32 s98, s76, 1
	s_sub_i32 s99, s77, s94
	s_cmp_ge_u32 s77, s94
	s_cselect_b32 s76, s98, s76
	s_cselect_b32 s77, s99, s77
	s_mul_i32 s84, s86, s76
	s_min_u32 s98, s86, s77
	s_add_u32 s84, s84, s98
	s_cmp_lt_u32 s86, s77
	s_addc_u32 s87, s84, s76
	s_min_u32 s84, s84, 0x2b00
	s_min_u32 s87, s87, 0x2b00
	s_lshl_b32 s84, s84, 4
	s_lshl_b32 s87, s87, 4
	s_mov_b32 s89, 0
	s_mov_b32 s32, 0
	s_lshr_b32 s77, s84, 5
	s_mul_i32 s77, s77, 0x17d07
	s_lshr_b32 s77, s77, 22
	s_min_u32 s77, s77, 0x7f
	s_lshl_b32 s75, s77, 7
	s_add_u32 s75, s75, 0xc0000
	v_and_b32_e32 v240, 0x70, v223
	v_add_u32_e32 v240, s75, v240
	global_load_dwordx4 v[240:243], v240, s[96:97]
	s_abs_i32 s8, s92
	v_cvt_f32_u32_e32 v0, s8
	s_sub_i32 s9, 0, s8
	s_ashr_i32 s3, s92, 31
	s_mov_b32 s14, 0
	v_rcp_iflag_f32_e32 v0, v0
	v_mov_b32_e32 v221, v245
	v_mov_b32_e32 v222, v249
	v_mul_f32_e32 v1, 0x4f7ffffe, v0
	v_cvt_u32_f32_e32 v1, v1
	s_nop 0
	v_readfirstlane_b32 s6, v1
	s_mul_i32 s7, s9, s6
	s_mul_hi_u32 s7, s6, s7
	s_add_i32 s6, s6, s7
	s_mul_hi_u32 s6, s6, 0xac0
	s_mul_i32 s7, s6, s8
	s_sub_i32 s7, 0xac0, s7
	s_add_i32 s10, s6, 1
	s_sub_i32 s11, s7, s8
	s_cmp_ge_u32 s7, s8
	s_cselect_b32 s6, s10, s6
	s_cselect_b32 s7, s11, s7
	s_add_i32 s10, s6, 1
	s_cmp_ge_u32 s7, s8
	s_cselect_b32 s6, s10, s6
	s_xor_b32 s6, s6, s3
	s_sub_i32 s10, s6, s3
	s_mul_i32 s3, s10, s92
	s_sub_i32 s11, 0xac0, s3
	s_sub_i32 s3, s2, s11
	s_ashr_i32 s6, s3, 31
	s_and_b32 s6, s6, s92
	s_add_i32 s3, s6, s3
	s_cmpk_lg_i32 s92, 0x100
	s_cselect_b64 s[6:7], -1, 0
	s_and_b64 vcc, exec, s[6:7]
	s_cbranch_vccz .LBB0_1206
	s_cmpk_gt_i32 s3, 0x157
	s_cbranch_scc1 .LBB0_1205
	v_mul_f32_e32 v0, 0x4f7ffffe, v0
	v_cvt_u32_f32_e32 v0, v0
	s_sub_i32 s14, s92, s3
	s_add_i32 s15, s14, 0x157
	s_sub_i32 s14, 0xfffffea9, s14
	s_xor_b32 s16, s15, s92
	s_max_i32 s14, s15, s14
	v_readfirstlane_b32 s15, v0
	s_mul_i32 s9, s9, s15
	s_mul_hi_u32 s9, s15, s9
	s_add_i32 s15, s15, s9
	s_mul_hi_u32 s9, s14, s15
	s_mul_i32 s15, s9, s8
	s_sub_i32 s14, s14, s15
	s_ashr_i32 s16, s16, 31
	s_add_i32 s15, s9, 1
	s_sub_i32 s17, s14, s8
	s_cmp_ge_u32 s14, s8
	s_cselect_b32 s9, s15, s9
	s_cselect_b32 s14, s17, s14
	s_add_i32 s15, s9, 1
	s_cmp_ge_u32 s14, s8
	s_cselect_b32 s8, s15, s9
	s_xor_b32 s8, s8, s16
	s_sub_i32 s8, s8, s16
	s_max_i32 s14, s8, 0

.LBB0_1221:
	s_add_u32 s14, s96, 0xa0000
	s_addc_u32 s15, s97, 0
	s_add_u32 s16, s96, 0x80000
	s_addc_u32 s17, s97, 0
	s_lshl_b32 s20, s20, 5
	s_and_b32 s50, s20, 0x60
	s_mov_b64 s[20:21], 0x80
	s_add_i32 m0, s45, 0x18000
	v_lshl_add_u64 v[6:7], v[6:7], 0, s[20:21]
	s_lshl_b32 s49, s8, 6
	s_lshl_b32 s8, s8, 13
	s_lshl_b32 s23, s50, 7
	s_waitcnt vmcnt(2)
	s_barrier
	global_load_lds_dwordx4 v[6:7], off
	v_lshl_add_u64 v[4:5], v[4:5], 0, s[20:21]
	s_add_i32 m0, s45, 0x1a000
	s_add_i32 s51, s45, 0x8000
	s_add_i32 s52, s45, 0xa000
	global_load_lds_dwordx4 v[4:5], off
	v_lshl_add_u64 v[0:1], v[0:1], 0, s[20:21]
	s_mov_b32 m0, s51
	s_add_u32 s24, s38, 0x80080
	global_load_lds_dwordx4 v[0:1], off
	v_lshl_add_u64 v[0:1], v[2:3], 0, s[20:21]
	s_mov_b32 m0, s52
	s_addc_u32 s25, s39, 0
	global_load_lds_dwordx4 v[0:1], off
	s_add_i32 m0, s45, 0x1c000
	v_lshl_add_u64 v[0:1], s[24:25], 0, v[130:131]
	global_load_lds_dwordx4 v[0:1], off
	v_lshl_add_u64 v[0:1], s[24:25], 0, v[134:135]
	s_add_i32 m0, s45, 0x1e000
	v_bfe_u32 v176, v8, 4, 2
	global_load_lds_dwordx4 v[0:1], off
	v_and_b32_e32 v175, 15, v8
	v_lshlrev_b32_e32 v0, 4, v176
	v_lshlrev_b32_e32 v1, 2, v8
	v_lshl_or_b32 v0, v175, 6, v0
	v_and_b32_e32 v1, 32, v1
	v_bitop3_b32 v2, v0, s8, v1 bitop3:0xde
	v_bitop3_b32 v177, v0, s23, v1 bitop3:0xde
	v_lshlrev_b32_e32 v0, 15, v9
	v_and_b32_e32 v0, 0xffff0000, v0
	v_lshl_add_u32 v0, v10, 12, v0
	v_and_b32_e32 v1, 1, v9
	v_lshl_or_b32 v0, v1, 6, v0
	v_lshl_add_u32 v136, v11, 1, v0
	v_lshlrev_b32_e32 v0, 15, v12
	v_and_b32_e32 v0, 0xffff0000, v0
	s_waitcnt vmcnt(6)
	s_cmpk_lt_u32 s22, 0x100
	v_lshl_add_u32 v0, v13, 12, v0
	v_and_b32_e32 v1, 1, v12
	s_cselect_b64 s[22:23], -1, 0
	s_cmp_lt_i32 s3, 64
	v_lshl_or_b32 v0, v1, 6, v0
	s_cselect_b64 s[24:25], -1, 0
	s_lshl_b32 s53, s3, 2
	s_add_i32 s54, s3, 0xc0
	v_mov_b32_e32 v137, v131
	v_lshl_add_u32 v138, v14, 1, v0
	v_mov_b32_e32 v139, v131
	s_add_i32 s55, 0, 0x10000
	s_add_i32 s60, 0, 0x14000
	v_add_u32_e32 v178, 0, v2
	s_mov_b32 s26, 0x3c010204
	s_mov_b32 s61, 0x15800
	s_movk_i32 s62, 0x5600
	s_mov_b32 s63, 0
	s_barrier
	s_cmp_lt_u32 s84, s87
	s_cbranch_scc0 .Lq_init_done
	s_mov_b32 s75, 0x42fe0000
	v_div_scale_f32 v236, vcc, v240, v240, s75
	v_rcp_f32_e32 v237, v236
	s_nop 1
	v_fma_f32 v238, -v236, v237, 1.0
	v_fmac_f32_e32 v237, v238, v237
	v_div_scale_f32 v238, vcc, s75, v240, s75
	v_mul_f32_e32 v239, v238, v237
	v_fma_f32 v244, -v236, v239, v238
	v_fmac_f32_e32 v239, v244, v237
	v_fma_f32 v236, -v236, v239, v238
	s_nop 4
	v_div_fmas_f32 v236, v236, v237, v239
	v_div_fixup_f32 v236, v236, v240, s75
	v_cmp_lt_f32_e32 vcc, 0, v240
	s_nop 1
	v_cndmask_b32_e32 v220, 0, v236, vcc
	v_div_scale_f32 v236, vcc, v241, v241, s75
	v_rcp_f32_e32 v237, v236
	s_nop 1
	v_fma_f32 v238, -v236, v237, 1.0
	v_fmac_f32_e32 v237, v238, v237
	v_div_scale_f32 v238, vcc, s75, v241, s75
	v_mul_f32_e32 v239, v238, v237
	v_fma_f32 v244, -v236, v239, v238
	v_fmac_f32_e32 v239, v244, v237
	v_fma_f32 v236, -v236, v239, v238
	s_nop 4
	v_div_fmas_f32 v236, v236, v237, v239
	v_div_fixup_f32 v236, v236, v241, s75
	v_cmp_lt_f32_e32 vcc, 0, v241
	s_nop 1
	v_cndmask_b32_e32 v225, 0, v236, vcc
	v_div_scale_f32 v236, vcc, v242, v242, s75
	v_rcp_f32_e32 v237, v236
	s_nop 1
	v_fma_f32 v238, -v236, v237, 1.0
	v_fmac_f32_e32 v237, v238, v237
	v_div_scale_f32 v238, vcc, s75, v242, s75
	v_mul_f32_e32 v239, v238, v237
	v_fma_f32 v244, -v236, v239, v238
	v_fmac_f32_e32 v239, v244, v237
	v_fma_f32 v236, -v236, v239, v238
	s_nop 4
	v_div_fmas_f32 v236, v236, v237, v239
	v_div_fixup_f32 v236, v236, v242, s75
	v_cmp_lt_f32_e32 vcc, 0, v242
	s_nop 1
	v_cndmask_b32_e32 v252, 0, v236, vcc
	v_div_scale_f32 v236, vcc, v243, v243, s75
	v_rcp_f32_e32 v237, v236
	s_nop 1
	v_fma_f32 v238, -v236, v237, 1.0
	v_fmac_f32_e32 v237, v238, v237
	v_div_scale_f32 v238, vcc, s75, v243, s75
	v_mul_f32_e32 v239, v238, v237
	v_fma_f32 v244, -v236, v239, v238
	v_fmac_f32_e32 v239, v244, v237
	v_fma_f32 v236, -v236, v239, v238
	s_nop 4
	v_div_fmas_f32 v236, v236, v237, v239
	v_div_fixup_f32 v236, v236, v243, s75
	v_cmp_lt_f32_e32 vcc, 0, v243
	s_nop 1
	v_cndmask_b32_e32 v253, 0, v236, vcc
	s_lshr_b32 s76, s84, 4
	s_lshr_b32 s77, s76, 1
	s_mul_i32 s77, s77, 0x17d07
	s_lshr_b32 s77, s77, 22
	s_add_u32 s89, s77, 1
	s_mul_i32 s89, s89, 0x560
	s_mul_i32 s75, s77, 86
	s_sub_u32 s76, s76, s75
	s_lshl_b32 s76, s76, 7
	s_mul_i32 s98, s77, 0x56000
	s_add_u32 s98, s98, s76
	s_add_u32 s98, s96, s98
	s_addc_u32 s99, s97, 0
	s_and_b32 s75, s84, 15
	s_add_u32 s76, s76, s75
	s_lshl_b32 s76, s76, 14
	s_lshl_b32 s77, s77, 7
	s_add_u32 s76, s76, s77
	s_load_dwordx2 s[100:101], s[0:1], 0x88
	s_waitcnt lgkmcnt(0)
	s_add_u32 s100, s100, s76
	s_addc_u32 s101, s101, 0
	s_mov_b32 s32, 1

.Lq_body_L:
	s_add_i32 s74, s38, 2
	s_add_u32 s39, s36, 0xfff80080
	s_addc_u32 s40, s37, -1
	s_cmp_eq_u32 s71, s38
	s_cselect_b32 s41, s67, s40
	s_cselect_b32 s40, s68, s39
	v_add_u32_e32 v152, s55, v177
	v_add_u32_e32 v168, s60, v177
	ds_read_b128 v[140:143], v152
	ds_read_b128 v[144:147], v152 offset:1024
	ds_read_b128 v[148:151], v152 offset:2048
	ds_read_b128 v[152:155], v152 offset:3072
	ds_read_b128 v[156:159], v168
	ds_read_b128 v[160:163], v168 offset:1024
	ds_read_b128 v[164:167], v168 offset:2048
	ds_read_b128 v[168:171], v168 offset:3072
	s_cselect_b32 s38, s70, s72
	s_cselect_b32 s39, s69, s73
	v_lshl_add_u64 v[172:173], s[36:37], 0, v[136:137]
	s_add_i32 m0, s45, 0xc000
	ds_read_b128 v[180:183], v178
	ds_read_b128 v[184:187], v178 offset:1024
	ds_read_b128 v[188:191], v178 offset:2048
	ds_read_b128 v[192:195], v178 offset:3072
	ds_read_b128 v[196:199], v178 offset:4096
	ds_read_b128 v[200:203], v178 offset:5120
	ds_read_b128 v[204:207], v178 offset:6144
	ds_read_b128 v[208:211], v178 offset:7168
	global_load_lds_dwordx4 v[172:173], off
	v_lshl_add_u64 v[172:173], s[36:37], 0, v[138:139]
	s_add_i32 m0, s45, 0xe000
	s_nop 0
	global_load_lds_dwordx4 v[172:173], off
	global_load_dwordx4 v[226:229], v223, s[100:101] nt
	s_add_u32 s84, s84, 1
	s_waitcnt vmcnt(9)
	s_waitcnt lgkmcnt(0)
	s_barrier
	s_setprio 1
	s_waitcnt lgkmcnt(0)
	v_mfma_i32_16x16x64_i8 v[124:127], v[140:143], v[180:183], v[124:127]
	v_mfma_i32_16x16x64_i8 v[120:123], v[148:151], v[180:183], v[120:123]
	v_mfma_i32_16x16x64_i8 v[116:119], v[140:143], v[188:191], v[116:119]
	v_mfma_i32_16x16x64_i8 v[112:115], v[148:151], v[188:191], v[112:115]
	v_mfma_i32_16x16x64_i8 v[104:107], v[140:143], v[196:199], v[104:107]
	v_mfma_i32_16x16x64_i8 v[96:99], v[148:151], v[196:199], v[96:99]
	v_mfma_i32_16x16x64_i8 v[88:91], v[140:143], v[204:207], v[88:91]
	v_mfma_i32_16x16x64_i8 v[80:83], v[148:151], v[204:207], v[80:83]
	v_mfma_i32_16x16x64_i8 v[124:127], v[144:147], v[184:187], v[124:127]
	v_mfma_i32_16x16x64_i8 v[120:123], v[152:155], v[184:187], v[120:123]
	v_mfma_i32_16x16x64_i8 v[116:119], v[144:147], v[192:195], v[116:119]
	v_mfma_i32_16x16x64_i8 v[112:115], v[152:155], v[192:195], v[112:115]
	v_mfma_i32_16x16x64_i8 v[104:107], v[144:147], v[200:203], v[104:107]
	v_mfma_i32_16x16x64_i8 v[96:99], v[152:155], v[200:203], v[96:99]
	v_mfma_i32_16x16x64_i8 v[88:91], v[144:147], v[208:211], v[88:91]
	v_mfma_i32_16x16x64_i8 v[80:83], v[152:155], v[208:211], v[80:83]
	s_setprio 0
	s_setprio 1
	v_mfma_i32_16x16x64_i8 v[108:111], v[156:159], v[180:183], v[108:111]
	v_mfma_i32_16x16x64_i8 v[100:103], v[164:167], v[180:183], v[100:103]
	v_mfma_i32_16x16x64_i8 v[92:95], v[156:159], v[188:191], v[92:95]
	v_mfma_i32_16x16x64_i8 v[84:87], v[164:167], v[188:191], v[84:87]
	v_mfma_i32_16x16x64_i8 v[76:79], v[156:159], v[196:199], v[76:79]
	v_mfma_i32_16x16x64_i8 v[72:75], v[164:167], v[196:199], v[72:75]
	v_mfma_i32_16x16x64_i8 v[68:71], v[156:159], v[204:207], v[68:71]
	v_mfma_i32_16x16x64_i8 v[64:67], v[164:167], v[204:207], v[64:67]
	v_mfma_i32_16x16x64_i8 v[108:111], v[160:163], v[184:187], v[108:111]
	v_mfma_i32_16x16x64_i8 v[100:103], v[168:171], v[184:187], v[100:103]
	v_mfma_i32_16x16x64_i8 v[92:95], v[160:163], v[192:195], v[92:95]
	v_mfma_i32_16x16x64_i8 v[84:87], v[168:171], v[192:195], v[84:87]
	v_mfma_i32_16x16x64_i8 v[76:79], v[160:163], v[200:203], v[76:79]
	v_mfma_i32_16x16x64_i8 v[72:75], v[168:171], v[200:203], v[72:75]
	v_mfma_i32_16x16x64_i8 v[68:71], v[160:163], v[208:211], v[68:71]
	v_mfma_i32_16x16x64_i8 v[64:67], v[168:171], v[208:211], v[64:67]
	s_setprio 0
	s_barrier
	s_add_i32 s75, s55, s42
	v_lshl_add_u64 v[172:173], s[38:39], 0, v[130:131]
	s_mov_b32 m0, s75
	ds_read_b128 v[180:183], v178 offset:16384
	ds_read_b128 v[184:187], v178 offset:17408
	ds_read_b128 v[188:191], v178 offset:18432
	ds_read_b128 v[192:195], v178 offset:19456
	ds_read_b128 v[196:199], v178 offset:20480
	ds_read_b128 v[200:203], v178 offset:21504
	ds_read_b128 v[204:207], v178 offset:22528
	ds_read_b128 v[208:211], v178 offset:23552
	global_load_lds_dwordx4 v[172:173], off
	s_add_i32 m0, s75, 0x2000
	s_add_u32 s76, s38, 0x80000
	v_lshl_add_u64 v[212:213], s[38:39], 0, v[134:135]
	s_addc_u32 s77, s39, 0
	s_add_i32 s75, s60, s42
	global_load_lds_dwordx4 v[212:213], off
	v_lshl_add_u64 v[214:215], s[76:77], 0, v[130:131]
	s_mov_b32 m0, s75
	v_lshl_add_u64 v[216:217], s[40:41], 0, v[132:133]
	global_load_lds_dwordx4 v[214:215], off
	v_lshl_add_u64 v[214:215], s[76:77], 0, v[134:135]
	s_add_i32 m0, s75, 0x2000
	s_nop 0
	global_load_lds_dwordx4 v[214:215], off
	v_lshl_add_u64 v[214:215], s[40:41], 0, v[128:129]
	s_mov_b32 m0, s45
	s_nop 0
	global_load_lds_dwordx4 v[214:215], off
	s_mov_b32 m0, s46
	s_nop 0
	global_load_lds_dwordx4 v[216:217], off
	s_waitcnt vmcnt(9)
	s_waitcnt lgkmcnt(0)
	s_barrier
	s_setprio 1
	s_waitcnt lgkmcnt(0)
	v_mfma_i32_16x16x64_i8 v[60:63], v[140:143], v[180:183], v[60:63]
	v_mfma_i32_16x16x64_i8 v[56:59], v[148:151], v[180:183], v[56:59]
	v_mfma_i32_16x16x64_i8 v[52:55], v[140:143], v[188:191], v[52:55]
	v_mfma_i32_16x16x64_i8 v[48:51], v[148:151], v[188:191], v[48:51]
	v_mfma_i32_16x16x64_i8 v[40:43], v[140:143], v[196:199], v[40:43]
	v_mfma_i32_16x16x64_i8 v[32:35], v[148:151], v[196:199], v[32:35]
	v_mfma_i32_16x16x64_i8 v[24:27], v[140:143], v[204:207], v[24:27]
	v_mfma_i32_16x16x64_i8 v[16:19], v[148:151], v[204:207], v[16:19]
	v_mfma_i32_16x16x64_i8 v[60:63], v[144:147], v[184:187], v[60:63]
	v_mfma_i32_16x16x64_i8 v[56:59], v[152:155], v[184:187], v[56:59]
	v_mfma_i32_16x16x64_i8 v[52:55], v[144:147], v[192:195], v[52:55]
	v_mfma_i32_16x16x64_i8 v[48:51], v[152:155], v[192:195], v[48:51]
	v_mfma_i32_16x16x64_i8 v[40:43], v[144:147], v[200:203], v[40:43]
	v_mfma_i32_16x16x64_i8 v[32:35], v[152:155], v[200:203], v[32:35]
	v_mfma_i32_16x16x64_i8 v[24:27], v[144:147], v[208:211], v[24:27]
	v_mfma_i32_16x16x64_i8 v[16:19], v[152:155], v[208:211], v[16:19]
	s_setprio 0
	s_setprio 1
	v_mfma_i32_16x16x64_i8 v[44:47], v[156:159], v[180:183], v[44:47]
	v_mfma_i32_16x16x64_i8 v[36:39], v[164:167], v[180:183], v[36:39]
	v_mfma_i32_16x16x64_i8 v[28:31], v[156:159], v[188:191], v[28:31]
	v_mfma_i32_16x16x64_i8 v[20:23], v[164:167], v[188:191], v[20:23]
	v_mfma_i32_16x16x64_i8 v[12:15], v[156:159], v[196:199], v[12:15]
	v_mfma_i32_16x16x64_i8 v[8:11], v[164:167], v[196:199], v[8:11]
	v_mfma_i32_16x16x64_i8 v[4:7], v[156:159], v[204:207], v[4:7]
	v_mfma_i32_16x16x64_i8 v[0:3], v[164:167], v[204:207], v[0:3]
	v_mfma_i32_16x16x64_i8 v[44:47], v[160:163], v[184:187], v[44:47]
	v_mfma_i32_16x16x64_i8 v[36:39], v[168:171], v[184:187], v[36:39]
	v_mfma_i32_16x16x64_i8 v[28:31], v[160:163], v[192:195], v[28:31]
	v_mfma_i32_16x16x64_i8 v[20:23], v[168:171], v[192:195], v[20:23]
	v_mfma_i32_16x16x64_i8 v[12:15], v[160:163], v[200:203], v[12:15]
	v_mfma_i32_16x16x64_i8 v[8:11], v[168:171], v[200:203], v[8:11]
	v_mfma_i32_16x16x64_i8 v[4:7], v[160:163], v[208:211], v[4:7]
	v_mfma_i32_16x16x64_i8 v[0:3], v[168:171], v[208:211], v[0:3]
	s_setprio 0
	s_barrier
	s_add_i32 s75, 0, 0x18000
	s_add_i32 s76, 0, 0x1c000
	v_add_u32_e32 v152, s75, v177
	v_add_u32_e32 v168, s76, v177
	ds_read_b128 v[140:143], v152
	ds_read_b128 v[144:147], v152 offset:1024
	ds_read_b128 v[148:151], v152 offset:2048
	ds_read_b128 v[152:155], v152 offset:3072
	ds_read_b128 v[156:159], v168
	ds_read_b128 v[160:163], v168 offset:1024
	ds_read_b128 v[164:167], v168 offset:2048
	ds_read_b128 v[168:171], v168 offset:3072
	s_add_u32 s40, s40, 0x80000
	s_addc_u32 s41, s41, 0
	s_mov_b32 m0, s47
	v_lshl_add_u64 v[218:219], s[40:41], 0, v[128:129]
	ds_read_b128 v[180:183], v178 offset:32768
	ds_read_b128 v[184:187], v178 offset:33792
	ds_read_b128 v[188:191], v178 offset:34816
	ds_read_b128 v[192:195], v178 offset:35840
	ds_read_b128 v[196:199], v178 offset:36864
	ds_read_b128 v[200:203], v178 offset:37888
	ds_read_b128 v[204:207], v178 offset:38912
	ds_read_b128 v[208:211], v178 offset:39936
	global_load_lds_dwordx4 v[218:219], off
	v_lshl_add_u64 v[218:219], s[40:41], 0, v[132:133]
	s_mov_b32 m0, s48
	s_nop 0
	global_load_lds_dwordx4 v[218:219], off
	s_waitcnt vmcnt(9)
	s_waitcnt lgkmcnt(0)
	s_barrier
	s_setprio 1
	s_waitcnt lgkmcnt(0)
	v_mfma_i32_16x16x64_i8 v[124:127], v[140:143], v[180:183], v[124:127]
	v_mfma_i32_16x16x64_i8 v[120:123], v[148:151], v[180:183], v[120:123]
	v_mfma_i32_16x16x64_i8 v[116:119], v[140:143], v[188:191], v[116:119]
	v_mfma_i32_16x16x64_i8 v[112:115], v[148:151], v[188:191], v[112:115]
	v_mfma_i32_16x16x64_i8 v[104:107], v[140:143], v[196:199], v[104:107]
	v_mfma_i32_16x16x64_i8 v[96:99], v[148:151], v[196:199], v[96:99]
	v_mfma_i32_16x16x64_i8 v[88:91], v[140:143], v[204:207], v[88:91]
	v_mfma_i32_16x16x64_i8 v[80:83], v[148:151], v[204:207], v[80:83]
	v_mfma_i32_16x16x64_i8 v[124:127], v[144:147], v[184:187], v[124:127]
	v_mfma_i32_16x16x64_i8 v[120:123], v[152:155], v[184:187], v[120:123]
	v_mfma_i32_16x16x64_i8 v[116:119], v[144:147], v[192:195], v[116:119]
	v_mfma_i32_16x16x64_i8 v[112:115], v[152:155], v[192:195], v[112:115]
	v_mfma_i32_16x16x64_i8 v[104:107], v[144:147], v[200:203], v[104:107]
	v_mfma_i32_16x16x64_i8 v[96:99], v[152:155], v[200:203], v[96:99]
	v_mfma_i32_16x16x64_i8 v[88:91], v[144:147], v[208:211], v[88:91]
	v_mfma_i32_16x16x64_i8 v[80:83], v[152:155], v[208:211], v[80:83]
	s_setprio 0
	s_setprio 1
	v_mfma_i32_16x16x64_i8 v[108:111], v[156:159], v[180:183], v[108:111]
	v_mfma_i32_16x16x64_i8 v[100:103], v[164:167], v[180:183], v[100:103]
	v_mfma_i32_16x16x64_i8 v[92:95], v[156:159], v[188:191], v[92:95]
	v_mfma_i32_16x16x64_i8 v[84:87], v[164:167], v[188:191], v[84:87]
	v_mfma_i32_16x16x64_i8 v[76:79], v[156:159], v[196:199], v[76:79]
	v_mfma_i32_16x16x64_i8 v[72:75], v[164:167], v[196:199], v[72:75]
	v_mfma_i32_16x16x64_i8 v[68:71], v[156:159], v[204:207], v[68:71]
	v_mfma_i32_16x16x64_i8 v[64:67], v[164:167], v[204:207], v[64:67]
	v_mfma_i32_16x16x64_i8 v[108:111], v[160:163], v[184:187], v[108:111]
	v_mfma_i32_16x16x64_i8 v[100:103], v[168:171], v[184:187], v[100:103]
	v_mfma_i32_16x16x64_i8 v[92:95], v[160:163], v[192:195], v[92:95]
	v_mfma_i32_16x16x64_i8 v[84:87], v[168:171], v[192:195], v[84:87]
	v_mfma_i32_16x16x64_i8 v[76:79], v[160:163], v[200:203], v[76:79]
	v_mfma_i32_16x16x64_i8 v[72:75], v[168:171], v[200:203], v[72:75]
	v_mfma_i32_16x16x64_i8 v[68:71], v[160:163], v[208:211], v[68:71]
	v_mfma_i32_16x16x64_i8 v[64:67], v[168:171], v[208:211], v[64:67]
	s_setprio 0
	s_barrier
	s_add_i32 s40, s75, s42
	v_lshl_add_u64 v[172:173], v[172:173], 0, s[20:21]
	s_mov_b32 m0, s40
	ds_read_b128 v[180:183], v178 offset:49152
	ds_read_b128 v[184:187], v178 offset:50176
	ds_read_b128 v[188:191], v178 offset:51200
	ds_read_b128 v[192:195], v178 offset:52224
	ds_read_b128 v[196:199], v178 offset:53248
	ds_read_b128 v[200:203], v178 offset:54272
	ds_read_b128 v[204:207], v178 offset:55296
	ds_read_b128 v[208:211], v178 offset:56320
	global_load_lds_dwordx4 v[172:173], off
	s_add_i32 m0, s40, 0x2000
	s_add_u32 s38, s38, 0x80080
	v_lshl_add_u64 v[172:173], v[212:213], 0, s[20:21]
	s_addc_u32 s39, s39, 0
	s_add_i32 s40, s76, s42
	global_load_lds_dwordx4 v[172:173], off
	v_lshl_add_u64 v[172:173], s[38:39], 0, v[130:131]
	s_mov_b32 m0, s40
	s_nop 0
	global_load_lds_dwordx4 v[172:173], off
	v_lshl_add_u64 v[172:173], s[38:39], 0, v[134:135]
	s_add_i32 m0, s40, 0x2000
	s_nop 0
	global_load_lds_dwordx4 v[172:173], off
	v_lshl_add_u64 v[172:173], v[214:215], 0, s[20:21]
	s_mov_b32 m0, s51
	s_nop 0
	global_load_lds_dwordx4 v[172:173], off
	v_lshl_add_u64 v[172:173], v[216:217], 0, s[20:21]
	s_mov_b32 m0, s52
	s_nop 0
	global_load_lds_dwordx4 v[172:173], off
	s_waitcnt vmcnt(8)
	s_waitcnt lgkmcnt(0)
	s_barrier
	s_setprio 1
	s_waitcnt lgkmcnt(0)
	v_mfma_i32_16x16x64_i8 v[60:63], v[140:143], v[180:183], v[60:63]
	v_mfma_i32_16x16x64_i8 v[56:59], v[148:151], v[180:183], v[56:59]
	v_mfma_i32_16x16x64_i8 v[52:55], v[140:143], v[188:191], v[52:55]
	v_fmaak_f32 v226, v226, v220, 0x4b400000
	v_mfma_i32_16x16x64_i8 v[48:51], v[148:151], v[188:191], v[48:51]
	v_mfma_i32_16x16x64_i8 v[40:43], v[140:143], v[196:199], v[40:43]
	v_mfma_i32_16x16x64_i8 v[32:35], v[148:151], v[196:199], v[32:35]
	v_fmaak_f32 v227, v227, v225, 0x4b400000
	v_mfma_i32_16x16x64_i8 v[24:27], v[140:143], v[204:207], v[24:27]
	v_mfma_i32_16x16x64_i8 v[16:19], v[148:151], v[204:207], v[16:19]
	v_mfma_i32_16x16x64_i8 v[60:63], v[144:147], v[184:187], v[60:63]
	v_fmaak_f32 v228, v228, v252, 0x4b400000
	v_mfma_i32_16x16x64_i8 v[56:59], v[152:155], v[184:187], v[56:59]
	v_mfma_i32_16x16x64_i8 v[52:55], v[144:147], v[192:195], v[52:55]
	v_mfma_i32_16x16x64_i8 v[48:51], v[152:155], v[192:195], v[48:51]
	v_fmaak_f32 v229, v229, v253, 0x4b400000
	v_mfma_i32_16x16x64_i8 v[40:43], v[144:147], v[200:203], v[40:43]
	v_mfma_i32_16x16x64_i8 v[32:35], v[152:155], v[200:203], v[32:35]
	v_mfma_i32_16x16x64_i8 v[24:27], v[144:147], v[208:211], v[24:27]
	v_alignbit_b32 v239, v226, v239, 8
	v_mfma_i32_16x16x64_i8 v[16:19], v[152:155], v[208:211], v[16:19]
	s_setprio 0
	s_setprio 1
	v_mfma_i32_16x16x64_i8 v[44:47], v[156:159], v[180:183], v[44:47]
	v_mfma_i32_16x16x64_i8 v[36:39], v[164:167], v[180:183], v[36:39]
	v_alignbit_b32 v243, v227, v243, 8
	v_mfma_i32_16x16x64_i8 v[28:31], v[156:159], v[188:191], v[28:31]
	v_mfma_i32_16x16x64_i8 v[20:23], v[164:167], v[188:191], v[20:23]
	v_mfma_i32_16x16x64_i8 v[12:15], v[156:159], v[196:199], v[12:15]
	v_alignbit_b32 v247, v228, v247, 8
	v_mfma_i32_16x16x64_i8 v[8:11], v[164:167], v[196:199], v[8:11]
	v_mfma_i32_16x16x64_i8 v[4:7], v[156:159], v[204:207], v[4:7]
	v_mfma_i32_16x16x64_i8 v[0:3], v[164:167], v[204:207], v[0:3]
	v_alignbit_b32 v251, v229, v251, 8
	v_mfma_i32_16x16x64_i8 v[44:47], v[160:163], v[184:187], v[44:47]
	v_mfma_i32_16x16x64_i8 v[36:39], v[168:171], v[184:187], v[36:39]
	v_mfma_i32_16x16x64_i8 v[28:31], v[160:163], v[192:195], v[28:31]
	v_add_u32_e32 v223, 0x4000, v223
	v_mfma_i32_16x16x64_i8 v[20:23], v[168:171], v[192:195], v[20:23]
	v_mfma_i32_16x16x64_i8 v[12:15], v[160:163], v[200:203], v[12:15]
	v_mfma_i32_16x16x64_i8 v[8:11], v[168:171], v[200:203], v[8:11]
	v_mfma_i32_16x16x64_i8 v[4:7], v[160:163], v[208:211], v[4:7]
	v_mfma_i32_16x16x64_i8 v[0:3], v[168:171], v[208:211], v[0:3]
	s_setprio 0
	s_barrier
	s_and_b32 s77, s84, 3
	s_cbranch_scc0 .Lq_mv_L

.Lq_body_ST:
	s_add_i32 s74, s38, 2
	s_add_u32 s39, s36, 0xfff80080
	s_addc_u32 s40, s37, -1
	s_cmp_eq_u32 s71, s38
	s_cselect_b32 s41, s67, s40
	s_cselect_b32 s40, s68, s39
	v_add_u32_e32 v152, s55, v177
	v_add_u32_e32 v168, s60, v177
	ds_read_b128 v[140:143], v152
	ds_read_b128 v[144:147], v152 offset:1024
	ds_read_b128 v[148:151], v152 offset:2048
	ds_read_b128 v[152:155], v152 offset:3072
	ds_read_b128 v[156:159], v168
	ds_read_b128 v[160:163], v168 offset:1024
	ds_read_b128 v[164:167], v168 offset:2048
	ds_read_b128 v[168:171], v168 offset:3072
	s_cselect_b32 s38, s70, s72
	s_cselect_b32 s39, s69, s73
	v_lshl_add_u64 v[172:173], s[36:37], 0, v[136:137]
	s_add_i32 m0, s45, 0xc000
	ds_read_b128 v[180:183], v178
	ds_read_b128 v[184:187], v178 offset:1024
	ds_read_b128 v[188:191], v178 offset:2048
	ds_read_b128 v[192:195], v178 offset:3072
	ds_read_b128 v[196:199], v178 offset:4096
	ds_read_b128 v[200:203], v178 offset:5120
	ds_read_b128 v[204:207], v178 offset:6144
	ds_read_b128 v[208:211], v178 offset:7168
	global_load_lds_dwordx4 v[172:173], off
	v_lshl_add_u64 v[172:173], s[36:37], 0, v[138:139]
	s_add_i32 m0, s45, 0xe000
	s_nop 0
	global_load_lds_dwordx4 v[172:173], off
	global_store_dwordx4 v224, v[236:239], s[98:99]
	s_add_u32 s98, s98, 0x2b00
	s_addc_u32 s99, s99, 0
	global_store_dwordx4 v224, v[240:243], s[98:99]
	s_add_u32 s98, s98, 0x2b00
	s_addc_u32 s99, s99, 0
	global_store_dwordx4 v224, v[244:247], s[98:99]
	s_add_u32 s98, s98, 0x2b00
	s_addc_u32 s99, s99, 0
	global_store_dwordx4 v224, v[248:251], s[98:99]
	v_subrev_u32_e32 v223, 0x40000, v223
	s_cmp_lt_u32 s84, s87
	s_cbranch_scc0 .Lq_st_last
	s_cmp_lt_u32 s84, s89
	s_cbranch_scc0 .Lq_st_full
	s_sub_u32 s98, s98, 0x8080
	s_subb_u32 s99, s99, 0
	s_add_u32 s100, s100, 0x200000
	s_addc_u32 s101, s101, 0
.Lq_st_go:
	global_load_dwordx4 v[226:229], v223, s[100:101] nt
	s_add_u32 s84, s84, 1
	s_mov_b32 s32, 1
	s_branch .Lq_st_j

.Lq_st_j:
	s_waitcnt vmcnt(13)
	s_waitcnt lgkmcnt(0)
	s_barrier
	s_setprio 1
	s_waitcnt lgkmcnt(0)
	v_mfma_i32_16x16x64_i8 v[124:127], v[140:143], v[180:183], v[124:127]
	v_mfma_i32_16x16x64_i8 v[120:123], v[148:151], v[180:183], v[120:123]
	v_mfma_i32_16x16x64_i8 v[116:119], v[140:143], v[188:191], v[116:119]
	v_mfma_i32_16x16x64_i8 v[112:115], v[148:151], v[188:191], v[112:115]
	v_mfma_i32_16x16x64_i8 v[104:107], v[140:143], v[196:199], v[104:107]
	v_mfma_i32_16x16x64_i8 v[96:99], v[148:151], v[196:199], v[96:99]
	v_mfma_i32_16x16x64_i8 v[88:91], v[140:143], v[204:207], v[88:91]
	v_mfma_i32_16x16x64_i8 v[80:83], v[148:151], v[204:207], v[80:83]
	v_mfma_i32_16x16x64_i8 v[124:127], v[144:147], v[184:187], v[124:127]
	v_mfma_i32_16x16x64_i8 v[120:123], v[152:155], v[184:187], v[120:123]
	v_mfma_i32_16x16x64_i8 v[116:119], v[144:147], v[192:195], v[116:119]
	v_mfma_i32_16x16x64_i8 v[112:115], v[152:155], v[192:195], v[112:115]
	v_mfma_i32_16x16x64_i8 v[104:107], v[144:147], v[200:203], v[104:107]
	v_mfma_i32_16x16x64_i8 v[96:99], v[152:155], v[200:203], v[96:99]
	v_mfma_i32_16x16x64_i8 v[88:91], v[144:147], v[208:211], v[88:91]
	v_mfma_i32_16x16x64_i8 v[80:83], v[152:155], v[208:211], v[80:83]
	s_setprio 0
	s_setprio 1
	v_mfma_i32_16x16x64_i8 v[108:111], v[156:159], v[180:183], v[108:111]
	v_mfma_i32_16x16x64_i8 v[100:103], v[164:167], v[180:183], v[100:103]
	v_mfma_i32_16x16x64_i8 v[92:95], v[156:159], v[188:191], v[92:95]
	v_mfma_i32_16x16x64_i8 v[84:87], v[164:167], v[188:191], v[84:87]
	v_mfma_i32_16x16x64_i8 v[76:79], v[156:159], v[196:199], v[76:79]
	v_mfma_i32_16x16x64_i8 v[72:75], v[164:167], v[196:199], v[72:75]
	v_mfma_i32_16x16x64_i8 v[68:71], v[156:159], v[204:207], v[68:71]
	v_mfma_i32_16x16x64_i8 v[64:67], v[164:167], v[204:207], v[64:67]
	v_mfma_i32_16x16x64_i8 v[108:111], v[160:163], v[184:187], v[108:111]
	v_mfma_i32_16x16x64_i8 v[100:103], v[168:171], v[184:187], v[100:103]
	v_mfma_i32_16x16x64_i8 v[92:95], v[160:163], v[192:195], v[92:95]
	v_mfma_i32_16x16x64_i8 v[84:87], v[168:171], v[192:195], v[84:87]
	v_mfma_i32_16x16x64_i8 v[76:79], v[160:163], v[200:203], v[76:79]
	v_mfma_i32_16x16x64_i8 v[72:75], v[168:171], v[200:203], v[72:75]
	v_mfma_i32_16x16x64_i8 v[68:71], v[160:163], v[208:211], v[68:71]
	v_mfma_i32_16x16x64_i8 v[64:67], v[168:171], v[208:211], v[64:67]
	s_setprio 0
	s_barrier
	s_add_i32 s75, s55, s42
	v_lshl_add_u64 v[172:173], s[38:39], 0, v[130:131]
	s_mov_b32 m0, s75
	ds_read_b128 v[180:183], v178 offset:16384
	ds_read_b128 v[184:187], v178 offset:17408
	ds_read_b128 v[188:191], v178 offset:18432
	ds_read_b128 v[192:195], v178 offset:19456
	ds_read_b128 v[196:199], v178 offset:20480
	ds_read_b128 v[200:203], v178 offset:21504
	ds_read_b128 v[204:207], v178 offset:22528
	ds_read_b128 v[208:211], v178 offset:23552
	global_load_lds_dwordx4 v[172:173], off
	s_add_i32 m0, s75, 0x2000
	s_add_u32 s76, s38, 0x80000
	v_lshl_add_u64 v[212:213], s[38:39], 0, v[134:135]
	s_addc_u32 s77, s39, 0
	s_add_i32 s75, s60, s42
	global_load_lds_dwordx4 v[212:213], off
	v_lshl_add_u64 v[214:215], s[76:77], 0, v[130:131]
	s_mov_b32 m0, s75
	v_lshl_add_u64 v[216:217], s[40:41], 0, v[132:133]
	global_load_lds_dwordx4 v[214:215], off
	v_lshl_add_u64 v[214:215], s[76:77], 0, v[134:135]
	s_add_i32 m0, s75, 0x2000
	s_nop 0
	global_load_lds_dwordx4 v[214:215], off
	v_lshl_add_u64 v[214:215], s[40:41], 0, v[128:129]
	s_mov_b32 m0, s45
	s_nop 0
	global_load_lds_dwordx4 v[214:215], off
	s_mov_b32 m0, s46
	s_nop 0
	global_load_lds_dwordx4 v[216:217], off
	s_waitcnt vmcnt(13)
	s_waitcnt lgkmcnt(0)
	s_barrier
	s_setprio 1
	s_waitcnt lgkmcnt(0)
	v_mfma_i32_16x16x64_i8 v[60:63], v[140:143], v[180:183], v[60:63]
	v_mfma_i32_16x16x64_i8 v[56:59], v[148:151], v[180:183], v[56:59]
	v_mfma_i32_16x16x64_i8 v[52:55], v[140:143], v[188:191], v[52:55]
	v_mfma_i32_16x16x64_i8 v[48:51], v[148:151], v[188:191], v[48:51]
	v_mfma_i32_16x16x64_i8 v[40:43], v[140:143], v[196:199], v[40:43]
	v_mfma_i32_16x16x64_i8 v[32:35], v[148:151], v[196:199], v[32:35]
	v_mfma_i32_16x16x64_i8 v[24:27], v[140:143], v[204:207], v[24:27]
	v_mfma_i32_16x16x64_i8 v[16:19], v[148:151], v[204:207], v[16:19]
	v_mfma_i32_16x16x64_i8 v[60:63], v[144:147], v[184:187], v[60:63]
	v_mfma_i32_16x16x64_i8 v[56:59], v[152:155], v[184:187], v[56:59]
	v_mfma_i32_16x16x64_i8 v[52:55], v[144:147], v[192:195], v[52:55]
	v_mfma_i32_16x16x64_i8 v[48:51], v[152:155], v[192:195], v[48:51]
	v_mfma_i32_16x16x64_i8 v[40:43], v[144:147], v[200:203], v[40:43]
	v_mfma_i32_16x16x64_i8 v[32:35], v[152:155], v[200:203], v[32:35]
	v_mfma_i32_16x16x64_i8 v[24:27], v[144:147], v[208:211], v[24:27]
	v_mfma_i32_16x16x64_i8 v[16:19], v[152:155], v[208:211], v[16:19]
	s_setprio 0
	s_setprio 1
	v_mfma_i32_16x16x64_i8 v[44:47], v[156:159], v[180:183], v[44:47]
	v_mfma_i32_16x16x64_i8 v[36:39], v[164:167], v[180:183], v[36:39]
	v_mfma_i32_16x16x64_i8 v[28:31], v[156:159], v[188:191], v[28:31]
	v_mfma_i32_16x16x64_i8 v[20:23], v[164:167], v[188:191], v[20:23]
	v_mfma_i32_16x16x64_i8 v[12:15], v[156:159], v[196:199], v[12:15]
	v_mfma_i32_16x16x64_i8 v[8:11], v[164:167], v[196:199], v[8:11]
	v_mfma_i32_16x16x64_i8 v[4:7], v[156:159], v[204:207], v[4:7]
	v_mfma_i32_16x16x64_i8 v[0:3], v[164:167], v[204:207], v[0:3]
	v_mfma_i32_16x16x64_i8 v[44:47], v[160:163], v[184:187], v[44:47]
	v_mfma_i32_16x16x64_i8 v[36:39], v[168:171], v[184:187], v[36:39]
	v_mfma_i32_16x16x64_i8 v[28:31], v[160:163], v[192:195], v[28:31]
	v_mfma_i32_16x16x64_i8 v[20:23], v[168:171], v[192:195], v[20:23]
	v_mfma_i32_16x16x64_i8 v[12:15], v[160:163], v[200:203], v[12:15]
	v_mfma_i32_16x16x64_i8 v[8:11], v[168:171], v[200:203], v[8:11]
	v_mfma_i32_16x16x64_i8 v[4:7], v[160:163], v[208:211], v[4:7]
	v_mfma_i32_16x16x64_i8 v[0:3], v[168:171], v[208:211], v[0:3]
	s_setprio 0
	s_barrier
	s_add_i32 s75, 0, 0x18000
	s_add_i32 s76, 0, 0x1c000
	v_add_u32_e32 v152, s75, v177
	v_add_u32_e32 v168, s76, v177
	ds_read_b128 v[140:143], v152
	ds_read_b128 v[144:147], v152 offset:1024
	ds_read_b128 v[148:151], v152 offset:2048
	ds_read_b128 v[152:155], v152 offset:3072
	ds_read_b128 v[156:159], v168
	ds_read_b128 v[160:163], v168 offset:1024
	ds_read_b128 v[164:167], v168 offset:2048
	ds_read_b128 v[168:171], v168 offset:3072
	s_add_u32 s40, s40, 0x80000
	s_addc_u32 s41, s41, 0
	s_mov_b32 m0, s47
	v_lshl_add_u64 v[218:219], s[40:41], 0, v[128:129]
	ds_read_b128 v[180:183], v178 offset:32768
	ds_read_b128 v[184:187], v178 offset:33792
	ds_read_b128 v[188:191], v178 offset:34816
	ds_read_b128 v[192:195], v178 offset:35840
	ds_read_b128 v[196:199], v178 offset:36864
	ds_read_b128 v[200:203], v178 offset:37888
	ds_read_b128 v[204:207], v178 offset:38912
	ds_read_b128 v[208:211], v178 offset:39936
	global_load_lds_dwordx4 v[218:219], off
	v_lshl_add_u64 v[218:219], s[40:41], 0, v[132:133]
	s_mov_b32 m0, s48
	s_nop 0
	global_load_lds_dwordx4 v[218:219], off
	s_waitcnt vmcnt(13)
	s_waitcnt lgkmcnt(0)
	s_barrier
	s_setprio 1
	s_waitcnt lgkmcnt(0)
	v_mfma_i32_16x16x64_i8 v[124:127], v[140:143], v[180:183], v[124:127]
	v_mfma_i32_16x16x64_i8 v[120:123], v[148:151], v[180:183], v[120:123]
	v_mfma_i32_16x16x64_i8 v[116:119], v[140:143], v[188:191], v[116:119]
	v_mfma_i32_16x16x64_i8 v[112:115], v[148:151], v[188:191], v[112:115]
	v_mfma_i32_16x16x64_i8 v[104:107], v[140:143], v[196:199], v[104:107]
	v_mfma_i32_16x16x64_i8 v[96:99], v[148:151], v[196:199], v[96:99]
	v_mfma_i32_16x16x64_i8 v[88:91], v[140:143], v[204:207], v[88:91]
	v_mfma_i32_16x16x64_i8 v[80:83], v[148:151], v[204:207], v[80:83]
	v_mfma_i32_16x16x64_i8 v[124:127], v[144:147], v[184:187], v[124:127]
	v_mfma_i32_16x16x64_i8 v[120:123], v[152:155], v[184:187], v[120:123]
	v_mfma_i32_16x16x64_i8 v[116:119], v[144:147], v[192:195], v[116:119]
	v_mfma_i32_16x16x64_i8 v[112:115], v[152:155], v[192:195], v[112:115]
	v_mfma_i32_16x16x64_i8 v[104:107], v[144:147], v[200:203], v[104:107]
	v_mfma_i32_16x16x64_i8 v[96:99], v[152:155], v[200:203], v[96:99]
	v_mfma_i32_16x16x64_i8 v[88:91], v[144:147], v[208:211], v[88:91]
	v_mfma_i32_16x16x64_i8 v[80:83], v[152:155], v[208:211], v[80:83]
	s_setprio 0
	s_setprio 1
	v_mfma_i32_16x16x64_i8 v[108:111], v[156:159], v[180:183], v[108:111]
	v_mfma_i32_16x16x64_i8 v[100:103], v[164:167], v[180:183], v[100:103]
	v_mfma_i32_16x16x64_i8 v[92:95], v[156:159], v[188:191], v[92:95]
	v_mfma_i32_16x16x64_i8 v[84:87], v[164:167], v[188:191], v[84:87]
	v_mfma_i32_16x16x64_i8 v[76:79], v[156:159], v[196:199], v[76:79]
	v_mfma_i32_16x16x64_i8 v[72:75], v[164:167], v[196:199], v[72:75]
	v_mfma_i32_16x16x64_i8 v[68:71], v[156:159], v[204:207], v[68:71]
	v_mfma_i32_16x16x64_i8 v[64:67], v[164:167], v[204:207], v[64:67]
	v_mfma_i32_16x16x64_i8 v[108:111], v[160:163], v[184:187], v[108:111]
	v_mfma_i32_16x16x64_i8 v[100:103], v[168:171], v[184:187], v[100:103]
	v_mfma_i32_16x16x64_i8 v[92:95], v[160:163], v[192:195], v[92:95]
	v_mfma_i32_16x16x64_i8 v[84:87], v[168:171], v[192:195], v[84:87]
	v_mfma_i32_16x16x64_i8 v[76:79], v[160:163], v[200:203], v[76:79]
	v_mfma_i32_16x16x64_i8 v[72:75], v[168:171], v[200:203], v[72:75]
	v_mfma_i32_16x16x64_i8 v[68:71], v[160:163], v[208:211], v[68:71]
	v_mfma_i32_16x16x64_i8 v[64:67], v[168:171], v[208:211], v[64:67]
	s_setprio 0
	s_barrier
	s_add_i32 s40, s75, s42
	v_lshl_add_u64 v[172:173], v[172:173], 0, s[20:21]
	s_mov_b32 m0, s40
	ds_read_b128 v[180:183], v178 offset:49152
	ds_read_b128 v[184:187], v178 offset:50176
	ds_read_b128 v[188:191], v178 offset:51200
	ds_read_b128 v[192:195], v178 offset:52224
	ds_read_b128 v[196:199], v178 offset:53248
	ds_read_b128 v[200:203], v178 offset:54272
	ds_read_b128 v[204:207], v178 offset:55296
	ds_read_b128 v[208:211], v178 offset:56320
	global_load_lds_dwordx4 v[172:173], off
	s_add_i32 m0, s40, 0x2000
	s_add_u32 s38, s38, 0x80080
	v_lshl_add_u64 v[172:173], v[212:213], 0, s[20:21]
	s_addc_u32 s39, s39, 0
	s_add_i32 s40, s76, s42
	global_load_lds_dwordx4 v[172:173], off
	v_lshl_add_u64 v[172:173], s[38:39], 0, v[130:131]
	s_mov_b32 m0, s40
	s_nop 0
	global_load_lds_dwordx4 v[172:173], off
	v_lshl_add_u64 v[172:173], s[38:39], 0, v[134:135]
	s_add_i32 m0, s40, 0x2000
	s_nop 0
	global_load_lds_dwordx4 v[172:173], off
	v_lshl_add_u64 v[172:173], v[214:215], 0, s[20:21]
	s_mov_b32 m0, s51
	s_nop 0
	global_load_lds_dwordx4 v[172:173], off
	v_lshl_add_u64 v[172:173], v[216:217], 0, s[20:21]
	s_mov_b32 m0, s52
	s_nop 0
	global_load_lds_dwordx4 v[172:173], off
	s_waitcnt vmcnt(8)
	s_waitcnt lgkmcnt(0)
	s_barrier
	s_setprio 1
	s_waitcnt lgkmcnt(0)
	v_mfma_i32_16x16x64_i8 v[60:63], v[140:143], v[180:183], v[60:63]
	v_mfma_i32_16x16x64_i8 v[56:59], v[148:151], v[180:183], v[56:59]
	v_mfma_i32_16x16x64_i8 v[52:55], v[140:143], v[188:191], v[52:55]
	v_fmaak_f32 v226, v226, v220, 0x4b400000
	v_mfma_i32_16x16x64_i8 v[48:51], v[148:151], v[188:191], v[48:51]
	v_mfma_i32_16x16x64_i8 v[40:43], v[140:143], v[196:199], v[40:43]
	v_mfma_i32_16x16x64_i8 v[32:35], v[148:151], v[196:199], v[32:35]
	v_fmaak_f32 v227, v227, v225, 0x4b400000
	v_mfma_i32_16x16x64_i8 v[24:27], v[140:143], v[204:207], v[24:27]
	v_mfma_i32_16x16x64_i8 v[16:19], v[148:151], v[204:207], v[16:19]
	v_mfma_i32_16x16x64_i8 v[60:63], v[144:147], v[184:187], v[60:63]
	v_fmaak_f32 v228, v228, v252, 0x4b400000
	v_mfma_i32_16x16x64_i8 v[56:59], v[152:155], v[184:187], v[56:59]
	v_mfma_i32_16x16x64_i8 v[52:55], v[144:147], v[192:195], v[52:55]
	v_mfma_i32_16x16x64_i8 v[48:51], v[152:155], v[192:195], v[48:51]
	v_fmaak_f32 v229, v229, v253, 0x4b400000
	v_mfma_i32_16x16x64_i8 v[40:43], v[144:147], v[200:203], v[40:43]
	v_mfma_i32_16x16x64_i8 v[32:35], v[152:155], v[200:203], v[32:35]
	v_mfma_i32_16x16x64_i8 v[24:27], v[144:147], v[208:211], v[24:27]
	v_alignbit_b32 v239, v226, v239, 8
	v_mfma_i32_16x16x64_i8 v[16:19], v[152:155], v[208:211], v[16:19]
	s_setprio 0
	s_setprio 1
	v_mfma_i32_16x16x64_i8 v[44:47], v[156:159], v[180:183], v[44:47]
	v_mfma_i32_16x16x64_i8 v[36:39], v[164:167], v[180:183], v[36:39]
	v_alignbit_b32 v243, v227, v243, 8
	v_mfma_i32_16x16x64_i8 v[28:31], v[156:159], v[188:191], v[28:31]
	v_mfma_i32_16x16x64_i8 v[20:23], v[164:167], v[188:191], v[20:23]
	v_mfma_i32_16x16x64_i8 v[12:15], v[156:159], v[196:199], v[12:15]
	v_alignbit_b32 v247, v228, v247, 8
	v_mfma_i32_16x16x64_i8 v[8:11], v[164:167], v[196:199], v[8:11]
	v_mfma_i32_16x16x64_i8 v[4:7], v[156:159], v[204:207], v[4:7]
	v_mfma_i32_16x16x64_i8 v[0:3], v[164:167], v[204:207], v[0:3]
	v_alignbit_b32 v251, v229, v251, 8
	v_mfma_i32_16x16x64_i8 v[44:47], v[160:163], v[184:187], v[44:47]
	v_mfma_i32_16x16x64_i8 v[36:39], v[168:171], v[184:187], v[36:39]
	v_mfma_i32_16x16x64_i8 v[28:31], v[160:163], v[192:195], v[28:31]
	v_add_u32_e32 v223, 0x4000, v223
	v_mfma_i32_16x16x64_i8 v[20:23], v[168:171], v[192:195], v[20:23]
	v_mfma_i32_16x16x64_i8 v[12:15], v[160:163], v[200:203], v[12:15]
	v_mfma_i32_16x16x64_i8 v[8:11], v[168:171], v[200:203], v[8:11]
	v_mfma_i32_16x16x64_i8 v[4:7], v[160:163], v[208:211], v[4:7]
	v_mfma_i32_16x16x64_i8 v[0:3], v[168:171], v[208:211], v[0:3]
	s_setprio 0
	s_barrier
	s_cmp_eq_u32 s32, 0
	s_cbranch_scc1 .Lq_mvx_ST
	s_and_b32 s77, s84, 3
	s_cbranch_scc0 .Lq_mv_ST

.Lq_st_full:
	s_lshr_b32 s76, s84, 4
	s_lshr_b32 s77, s76, 1
	s_mul_i32 s77, s77, 0x17d07
	s_lshr_b32 s77, s77, 22
	s_branch .Lq_newnb_ST
.Lq_nbok_ST:
	s_add_u32 s89, s77, 1
	s_mul_i32 s89, s89, 0x560
	s_mul_i32 s75, s77, 86
	s_sub_u32 s76, s76, s75
	s_lshl_b32 s76, s76, 7
	s_mul_i32 s98, s77, 0x56000
	s_add_u32 s98, s98, s76
	s_add_u32 s98, s96, s98
	s_addc_u32 s99, s97, 0
	s_and_b32 s75, s84, 15
	s_add_u32 s76, s76, s75
	s_lshl_b32 s76, s76, 14
	s_lshl_b32 s77, s77, 7
	s_add_u32 s76, s76, s77
	s_load_dwordx2 s[100:101], s[0:1], 0x88
	s_waitcnt lgkmcnt(0)
	s_add_u32 s100, s100, s76
	s_addc_u32 s101, s101, 0
	s_branch .Lq_st_go
.Lq_newnb_ST:
	s_lshl_b32 s75, s77, 7
	s_add_u32 s75, s75, 0xc0000
	v_and_b32_e32 v240, 0x70, v223
	v_add_u32_e32 v240, s75, v240
	global_load_dwordx4 v[240:243], v240, s[96:97]
	s_waitcnt vmcnt(0)
	s_mov_b32 s75, 0x42fe0000
	v_div_scale_f32 v236, vcc, v240, v240, s75
	v_rcp_f32_e32 v237, v236
	s_nop 1
	v_fma_f32 v238, -v236, v237, 1.0
	v_fmac_f32_e32 v237, v238, v237
	v_div_scale_f32 v238, vcc, s75, v240, s75
	v_mul_f32_e32 v239, v238, v237
	v_fma_f32 v244, -v236, v239, v238
	v_fmac_f32_e32 v239, v244, v237
	v_fma_f32 v236, -v236, v239, v238
	s_nop 4
	v_div_fmas_f32 v236, v236, v237, v239
	v_div_fixup_f32 v236, v236, v240, s75
	v_cmp_lt_f32_e32 vcc, 0, v240
	s_nop 1
	v_cndmask_b32_e32 v220, 0, v236, vcc
	v_div_scale_f32 v236, vcc, v241, v241, s75
	v_rcp_f32_e32 v237, v236
	s_nop 1
	v_fma_f32 v238, -v236, v237, 1.0
	v_fmac_f32_e32 v237, v238, v237
	v_div_scale_f32 v238, vcc, s75, v241, s75
	v_mul_f32_e32 v239, v238, v237
	v_fma_f32 v244, -v236, v239, v238
	v_fmac_f32_e32 v239, v244, v237
	v_fma_f32 v236, -v236, v239, v238
	s_nop 4
	v_div_fmas_f32 v236, v236, v237, v239
	v_div_fixup_f32 v236, v236, v241, s75
	v_cmp_lt_f32_e32 vcc, 0, v241
	s_nop 1
	v_cndmask_b32_e32 v225, 0, v236, vcc
	v_div_scale_f32 v236, vcc, v242, v242, s75
	v_rcp_f32_e32 v237, v236
	s_nop 1
	v_fma_f32 v238, -v236, v237, 1.0
	v_fmac_f32_e32 v237, v238, v237
	v_div_scale_f32 v238, vcc, s75, v242, s75
	v_mul_f32_e32 v239, v238, v237
	v_fma_f32 v244, -v236, v239, v238
	v_fmac_f32_e32 v239, v244, v237
	v_fma_f32 v236, -v236, v239, v238
	s_nop 4
	v_div_fmas_f32 v236, v236, v237, v239
	v_div_fixup_f32 v236, v236, v242, s75
	v_cmp_lt_f32_e32 vcc, 0, v242
	s_nop 1
	v_cndmask_b32_e32 v252, 0, v236, vcc
	v_div_scale_f32 v236, vcc, v243, v243, s75
	v_rcp_f32_e32 v237, v236
	s_nop 1
	v_fma_f32 v238, -v236, v237, 1.0
	v_fmac_f32_e32 v237, v238, v237
	v_div_scale_f32 v238, vcc, s75, v243, s75
	v_mul_f32_e32 v239, v238, v237
	v_fma_f32 v244, -v236, v239, v238
	v_fmac_f32_e32 v239, v244, v237
	v_fma_f32 v236, -v236, v239, v238
	s_nop 4
	v_div_fmas_f32 v236, v236, v237, v239
	v_div_fixup_f32 v236, v236, v243, s75
	v_cmp_lt_f32_e32 vcc, 0, v243
	s_nop 1
	v_cndmask_b32_e32 v253, 0, v236, vcc
	s_branch .Lq_nbok_ST

.LBB0_1250:
	s_and_b32 s75, s84, 15
	s_lshl_b32 s75, s75, 14
	v_subrev_u32_e32 v223, s75, v223
	s_cmp_eq_u32 s32, 2
	s_cbranch_scc0 .Lq_tail
	v_subrev_u32_e32 v223, 0x40000, v223

.Lq_t_nost:
	s_mov_b32 s32, 0
	s_cmp_lt_u32 s84, s87
	s_cbranch_scc0 .Lq_tail_done
	s_lshr_b32 s76, s84, 4
	s_lshr_b32 s77, s76, 1
	s_mul_i32 s77, s77, 0x17d07
	s_lshr_b32 s77, s77, 22
	s_cmp_lt_u32 s84, s89
	s_cbranch_scc0 .Lq_newnb_t
.Lq_nbok_t:
	s_add_u32 s89, s77, 1
	s_mul_i32 s89, s89, 0x560
	s_mul_i32 s75, s77, 86
	s_sub_u32 s76, s76, s75
	s_lshl_b32 s76, s76, 7
	s_mul_i32 s98, s77, 0x56000
	s_add_u32 s98, s98, s76
	s_add_u32 s98, s96, s98
	s_addc_u32 s99, s97, 0
	s_and_b32 s75, s84, 15
	s_add_u32 s76, s76, s75
	s_lshl_b32 s76, s76, 14
	s_lshl_b32 s77, s77, 7
	s_add_u32 s76, s76, s77
	s_load_dwordx2 s[100:101], s[0:1], 0x88
	s_waitcnt lgkmcnt(0)
	s_add_u32 s100, s100, s76
	s_addc_u32 s101, s101, 0
	global_load_dwordx4 v[226:229], v223, s[100:101] nt
	s_add_u32 s84, s84, 1
	s_waitcnt vmcnt(0)
	v_fmaak_f32 v226, v226, v220, 0x4b400000
	v_fmaak_f32 v227, v227, v225, 0x4b400000
	v_fmaak_f32 v228, v228, v252, 0x4b400000
	v_fmaak_f32 v229, v229, v253, 0x4b400000
	v_alignbit_b32 v239, v226, v239, 8
	v_alignbit_b32 v243, v227, v243, 8
	v_alignbit_b32 v247, v228, v247, 8
	v_alignbit_b32 v251, v229, v251, 8
	s_and_b32 s77, s84, 3
	s_cbranch_scc0 .Lq_mv_t
